# transposes loops (P0,P4): next-tile loads now overlap the transposed-read phase (gain select + vmcnt wait moved to the back edge); GEMM7 epilogue preloads all ssq_in vectors
# speedup vs baseline: 1.0630x; 1.0090x over previous
.LBB0_73:
	s_mov_b64 s[100:101], s[0:1]
.LBB0_74:
	v_lshlrev_b32_e32 v37, 2, v41
	v_add3_u32 v37, s66, v43, v37
	s_ashr_i32 s9, s8, 31
	v_add_u32_e32 v49, 0x400, v37
	v_add_u32_e32 v76, 0x800, v37
	v_add_u32_e32 v77, 0xc00, v37
	s_waitcnt lgkmcnt(0)
	s_barrier
	s_lshl_b64 s[0:1], s[8:9], 1
	ds_read2_b32 v[56:57], v37 offset1:32
	ds_read2_b32 v[58:59], v37 offset0:129 offset1:161
	ds_read2_b32 v[60:61], v49 offset0:2 offset1:34
	ds_read2_b32 v[62:63], v49 offset0:131 offset1:163
	ds_read2_b32 v[64:65], v76 offset0:4 offset1:36
	ds_read2_b32 v[66:67], v76 offset0:133 offset1:165
	ds_read2_b32 v[68:69], v77 offset0:6 offset1:38
	ds_read2_b32 v[70:71], v77 offset0:135 offset1:167
	s_add_u32 s0, s6, s0
	s_addc_u32 s1, s7, s1
	v_mov_b32_e32 v51, v35
	v_lshl_add_u64 v[72:73], s[0:1], 0, v[50:51]
	v_add_u32_e32 v51, s54, v41
	v_mad_i64_i32 v[74:75], s[0:1], s55, v51, 0
	s_waitcnt lgkmcnt(6)
	v_cvt_pk_bf16_f32 v52, v56, v58
	s_waitcnt lgkmcnt(4)
	v_cvt_pk_bf16_f32 v53, v60, v62
	s_waitcnt lgkmcnt(2)
	v_cvt_pk_bf16_f32 v54, v64, v66
	s_waitcnt lgkmcnt(0)
	v_cvt_pk_bf16_f32 v55, v68, v70
	v_lshl_add_u64 v[74:75], v[74:75], 1, v[72:73]
	global_store_dwordx4 v[74:75], v[52:55], off
	v_add_u32_e32 v56, 32, v51
	s_xor_b32 s63, s63, 1
	v_cvt_pk_bf16_f32 v52, v57, v59
	v_cvt_pk_bf16_f32 v53, v61, v63
	v_cvt_pk_bf16_f32 v54, v65, v67
	v_cvt_pk_bf16_f32 v55, v69, v71
	ds_read2_b32 v[58:59], v37 offset0:64 offset1:96
	ds_read2_b32 v[60:61], v37 offset0:193 offset1:225
	ds_read2_b32 v[62:63], v49 offset0:66 offset1:98
	ds_read2_b32 v[64:65], v49 offset0:195 offset1:227
	ds_read2_b32 v[66:67], v76 offset0:68 offset1:100
	ds_read2_b32 v[68:69], v76 offset0:197 offset1:229
	ds_read2_b32 v[70:71], v77 offset0:70 offset1:102
	ds_read2_b32 v[74:75], v77 offset0:199 offset1:231
	v_mad_i64_i32 v[56:57], s[0:1], s55, v56, 0
	v_lshl_add_u64 v[56:57], v[56:57], 1, v[72:73]
	v_add_u32_e32 v37, 64, v51
	global_store_dwordx4 v[56:57], v[52:55], off
	v_mad_i64_i32 v[56:57], s[0:1], s55, v37, 0
	s_waitcnt lgkmcnt(6)
	v_cvt_pk_bf16_f32 v52, v58, v60
	s_waitcnt lgkmcnt(4)
	v_cvt_pk_bf16_f32 v53, v62, v64
	s_waitcnt lgkmcnt(2)
	v_cvt_pk_bf16_f32 v54, v66, v68
	s_waitcnt lgkmcnt(0)
	v_cvt_pk_bf16_f32 v55, v70, v74
	v_lshl_add_u64 v[56:57], v[56:57], 1, v[72:73]
	v_add_u32_e32 v37, 0x60, v51
	global_store_dwordx4 v[56:57], v[52:55], off
	v_mad_i64_i32 v[56:57], s[0:1], s55, v37, 0
	s_nop 0
	v_cvt_pk_bf16_f32 v52, v59, v61
	v_cvt_pk_bf16_f32 v53, v63, v65
	v_cvt_pk_bf16_f32 v54, v67, v69
	v_cvt_pk_bf16_f32 v55, v71, v75
	v_lshl_add_u64 v[56:57], v[56:57], 1, v[72:73]
	s_add_i32 s56, s56, s57
	s_add_i32 s58, s58, s59
	s_add_i32 s60, s60, s61
	s_andn2_b64 vcc, exec, s[12:13]
	s_mov_b32 s54, s64
	s_mov_b64 s[6:7], s[34:35]
	s_mov_b32 s55, s5
	s_mov_b32 s8, s65
	global_store_dwordx4 v[56:57], v[52:55], off
	s_cbranch_vccz .LBB0_121
	s_waitcnt vmcnt(5)
	v_cndmask_b32_e64 v34, 0, v34, s[100:101]
	v_cndmask_b32_e64 v36, 0, v38, s[100:101]
	v_cndmask_b32_e64 v38, 0, v48, s[100:101]
	v_cndmask_b32_e64 v40, 0, v40, s[100:101]
	v_cndmask_b32_e64 v42, 0, v42, s[100:101]
	v_cndmask_b32_e64 v44, 0, v44, s[100:101]
	v_cndmask_b32_e64 v46, 0, v46, s[100:101]
	s_waitcnt vmcnt(4)
	v_cndmask_b32_e64 v48, 0, v78, s[100:101]

.LBB0_115:
	v_lshl_add_u64 v[28:29], v[24:25], 0, s[86:87]
	global_load_dwordx4 v[24:27], v[28:29], off
	v_mov_b32_e32 v78, 1.0
	s_and_b64 vcc, exec, s[2:3]
	v_mov_b32_e32 v34, 1.0
	s_cbranch_vccnz .LBB0_117
	global_load_dword v34, v[36:37], off offset:384
.LBB0_117:
	v_lshl_add_u64 v[28:29], v[28:29], 0, s[86:87]
	global_load_dwordx4 v[28:31], v[28:29], off
	s_and_b64 vcc, exec, s[2:3]
	s_cbranch_vccnz .LBB0_73
	global_load_dword v78, v[36:37], off offset:448
	s_branch .LBB0_73

.LBB0_805:
	v_lshlrev_b32_e32 v37, 2, v41
	v_add3_u32 v37, s41, v43, v37
	s_ashr_i32 s9, s8, 31
	v_add_u32_e32 v49, 0x400, v37
	v_add_u32_e32 v76, 0x800, v37
	v_add_u32_e32 v77, 0xc00, v37
	s_waitcnt lgkmcnt(0)
	s_barrier
	s_lshl_b64 s[0:1], s[8:9], 1
	ds_read2_b32 v[56:57], v37 offset1:32
	ds_read2_b32 v[58:59], v37 offset0:129 offset1:161
	ds_read2_b32 v[60:61], v49 offset0:2 offset1:34
	ds_read2_b32 v[62:63], v49 offset0:131 offset1:163
	ds_read2_b32 v[64:65], v76 offset0:4 offset1:36
	ds_read2_b32 v[66:67], v76 offset0:133 offset1:165
	ds_read2_b32 v[68:69], v77 offset0:6 offset1:38
	ds_read2_b32 v[70:71], v77 offset0:135 offset1:167
	s_add_u32 s0, s6, s0
	s_addc_u32 s1, s7, s1
	v_mov_b32_e32 v51, v35
	v_lshl_add_u64 v[72:73], s[0:1], 0, v[50:51]
	v_add_u32_e32 v51, s29, v41
	v_mad_i64_i32 v[74:75], s[0:1], s28, v51, 0
	s_waitcnt lgkmcnt(6)
	v_cvt_pk_bf16_f32 v52, v56, v58
	s_waitcnt lgkmcnt(4)
	v_cvt_pk_bf16_f32 v53, v60, v62
	s_waitcnt lgkmcnt(2)
	v_cvt_pk_bf16_f32 v54, v64, v66
	s_waitcnt lgkmcnt(0)
	v_cvt_pk_bf16_f32 v55, v68, v70
	v_lshl_add_u64 v[74:75], v[74:75], 1, v[72:73]
	global_store_dwordx4 v[74:75], v[52:55], off
	v_add_u32_e32 v56, 32, v51
	s_xor_b32 s34, s34, 1
	v_cvt_pk_bf16_f32 v52, v57, v59
	v_cvt_pk_bf16_f32 v53, v61, v63
	v_cvt_pk_bf16_f32 v54, v65, v67
	v_cvt_pk_bf16_f32 v55, v69, v71
	ds_read2_b32 v[58:59], v37 offset0:64 offset1:96
	ds_read2_b32 v[60:61], v37 offset0:193 offset1:225
	ds_read2_b32 v[62:63], v49 offset0:66 offset1:98
	ds_read2_b32 v[64:65], v49 offset0:195 offset1:227
	ds_read2_b32 v[66:67], v76 offset0:68 offset1:100
	ds_read2_b32 v[68:69], v76 offset0:197 offset1:229
	ds_read2_b32 v[70:71], v77 offset0:70 offset1:102
	ds_read2_b32 v[74:75], v77 offset0:199 offset1:231
	v_mad_i64_i32 v[56:57], s[0:1], s28, v56, 0
	v_lshl_add_u64 v[56:57], v[56:57], 1, v[72:73]
	v_add_u32_e32 v37, 64, v51
	global_store_dwordx4 v[56:57], v[52:55], off
	v_mad_i64_i32 v[56:57], s[0:1], s28, v37, 0
	s_waitcnt lgkmcnt(6)
	v_cvt_pk_bf16_f32 v52, v58, v60
	s_waitcnt lgkmcnt(4)
	v_cvt_pk_bf16_f32 v53, v62, v64
	s_waitcnt lgkmcnt(2)
	v_cvt_pk_bf16_f32 v54, v66, v68
	s_waitcnt lgkmcnt(0)
	v_cvt_pk_bf16_f32 v55, v70, v74
	v_lshl_add_u64 v[56:57], v[56:57], 1, v[72:73]
	v_add_u32_e32 v37, 0x60, v51
	global_store_dwordx4 v[56:57], v[52:55], off
	v_mad_i64_i32 v[56:57], s[0:1], s28, v37, 0
	s_addk_i32 s30, 0xbe
	s_addk_i32 s31, 0x5f00
	s_addk_i32 s33, 0x5f0
	v_cvt_pk_bf16_f32 v52, v59, v61
	v_cvt_pk_bf16_f32 v53, v63, v65
	v_cvt_pk_bf16_f32 v54, v67, v69
	v_cvt_pk_bf16_f32 v55, v71, v75
	v_lshl_add_u64 v[56:57], v[56:57], 1, v[72:73]
	s_cmpk_lt_i32 s40, 0xd52
	s_mov_b32 s29, s39
	s_mov_b64 s[6:7], s[22:23]
	s_mov_b32 s28, s38
	s_mov_b32 s8, s35
	global_store_dwordx4 v[56:57], v[52:55], off
	s_cbranch_scc0 .LBB0_829
	s_waitcnt vmcnt(5)
	v_cndmask_b32_e64 v34, 0, v34, s[100:101]
	v_cndmask_b32_e64 v36, 0, v38, s[100:101]
	v_cndmask_b32_e64 v38, 0, v48, s[100:101]
	v_cndmask_b32_e64 v40, 0, v40, s[100:101]
	v_cndmask_b32_e64 v42, 0, v42, s[100:101]
	v_cndmask_b32_e64 v44, 0, v44, s[100:101]
	v_cndmask_b32_e64 v46, 0, v46, s[100:101]
	s_waitcnt vmcnt(4)
	v_cndmask_b32_e64 v48, 0, v78, s[100:101]

.LBB0_825:
	v_lshl_add_u64 v[28:29], v[24:25], 0, s[24:25]
	global_load_dwordx4 v[24:27], v[28:29], off
	v_mov_b32_e32 v78, 1.0
	s_and_b64 vcc, exec, s[2:3]
	v_mov_b32_e32 v34, 1.0
	s_cbranch_vccnz .LBB0_827
	global_load_dword v34, v[36:37], off offset:384
.LBB0_827:
	v_lshl_add_u64 v[28:29], v[28:29], 0, s[24:25]
	global_load_dwordx4 v[28:31], v[28:29], off
	s_and_b64 vcc, exec, s[2:3]
	s_cbranch_vccnz .LBB0_804
	global_load_dword v78, v[36:37], off offset:448
	s_branch .LBB0_804

.LBB0_1111:
	s_or_b64 exec, exec, s[0:1]
	v_readlane_b32 s8, v237, 0
	v_lshlrev_b64 v[154:155], 2, v[142:143]
	v_readlane_b32 s9, v237, 1
	v_readlane_b32 s10, v237, 2
	v_readlane_b32 s11, v237, 3
	s_waitcnt lgkmcnt(0)
	s_barrier
	v_lshl_add_u64 v[156:157], s[8:9], 0, v[154:155]
	v_lshl_add_u64 v[158:159], s[26:27], 0, v[154:155]
	v_lshl_add_u64 v[160:161], s[28:29], 0, v[154:155]
	v_lshl_add_u64 v[162:163], s[30:31], 0, v[154:155]
	v_lshl_add_u64 v[164:165], s[34:35], 0, v[154:155]
	v_lshl_add_u64 v[166:167], s[38:39], 0, v[154:155]
	v_lshl_add_u64 v[154:155], s[10:11], 0, v[154:155]
	global_load_dwordx4 v[148:151], v[146:147], off
	global_load_dwordx4 v[208:211], v[146:147], off offset:64
	global_load_dwordx4 v[212:215], v[146:147], off offset:128
	global_load_dwordx4 v[216:219], v[146:147], off offset:192
	global_load_dwordx4 v[220:223], v[146:147], off offset:512
	global_load_dwordx4 v[224:227], v[146:147], off offset:576
	global_load_dwordx4 v[228:231], v[146:147], off offset:640
	global_load_dwordx4 v[232:235], v[146:147], off offset:704
	v_add_co_u32_e32 v168, vcc, s96, v154
	v_cmp_eq_u32_e64 s[8:9], 0, v153
	s_nop 0
	v_addc_co_u32_e32 v169, vcc, 0, v155, vcc
	global_load_dword v193, v[156:157], off
	global_load_dword v187, v[158:159], off
	global_load_dword v194, v[160:161], off
	global_load_dword v188, v[162:163], off
	global_load_dword v141, v[162:163], off offset:64
	global_load_dword v184, v[160:161], off offset:64
	global_load_dword v145, v[158:159], off offset:64
	global_load_dword v185, v[156:157], off offset:64
	global_load_dword v195, v[164:165], off
	global_load_dword v189, v[166:167], off
	global_load_dword v181, v[166:167], off offset:64
	global_load_dword v186, v[164:165], off offset:64
	global_load_dword v192, v[154:155], off
	global_load_dword v190, v[168:169], off offset:2048
	global_load_dword v182, v[168:169], off offset:2112
	global_load_dword v183, v[154:155], off offset:64
	v_mov_b64_e32 v[154:155], s[46:47]
	v_lshlrev_b32_e32 v153, 4, v153
	s_add_i32 s0, 0, 0x20000
	v_add3_u32 v153, v152, v153, 48
	v_lshl_add_u32 v196, v152, 2, s0
	v_add_u32_e32 v166, s83, v196
	v_readlane_b32 s12, v237, 4
	v_readlane_b32 s13, v237, 5
	v_readlane_b32 s14, v237, 6
	v_readlane_b32 s15, v237, 7
	s_waitcnt vmcnt(0)
	v_pk_fma_f32 v[150:151], v[150:151], s[42:43], v[154:155] op_sel_hi:[1,0,0]
	s_nop 0
	v_mul_f32_e32 v152, 0x4b800000, v150
	v_mul_f32_e32 v156, 0x4b800000, v151
	v_cmp_gt_f32_e32 vcc, s91, v150
	v_cmp_gt_f32_e64 s[0:1], s91, v151
	v_pk_fma_f32 v[148:149], v[148:149], s[42:43], v[154:155] op_sel_hi:[1,0,0]
	v_cndmask_b32_e32 v150, v150, v152, vcc
	v_cndmask_b32_e64 v151, v151, v156, s[0:1]
	v_rsq_f32_e32 v150, v150
	v_rsq_f32_e32 v151, v151
	v_and_b32_e32 v152, 63, v153
	v_and_or_b32 v152, v180, 64, v152
	v_lshlrev_b32_e32 v191, 2, v152
	v_pk_mul_f32 v[152:153], v[150:151], s[44:45] op_sel_hi:[1,0]
	s_nop 0
	v_cndmask_b32_e64 v157, v151, v153, s[0:1]
	v_cndmask_b32_e32 v156, v150, v152, vcc
	v_pk_mul_f32 v[152:153], v[62:63], v[156:157]
	v_pk_mul_f32 v[150:151], v[54:55], v[156:157]
	ds_bpermute_b32 v167, v191, v152
	ds_bpermute_b32 v168, v191, v153
	ds_bpermute_b32 v164, v191, v150
	ds_bpermute_b32 v165, v191, v151
	v_cmp_gt_f32_e32 vcc, s91, v149
	v_cmp_gt_f32_e64 s[0:1], s91, v148
	s_and_saveexec_b64 s[58:59], s[8:9]
	s_cbranch_execz .LBB0_1113
	ds_read2_b32 v[154:155], v166 offset1:32
	ds_read2_b32 v[158:159], v166 offset0:64 offset1:96
	s_waitcnt lgkmcnt(1)
	v_cndmask_b32_e64 v167, 0, v154, s[4:5]
	v_cndmask_b32_e64 v164, 0, v155, s[4:5]
	s_waitcnt lgkmcnt(0)
	v_cndmask_b32_e64 v168, 0, v158, s[4:5]
	v_cndmask_b32_e64 v165, 0, v159, s[4:5]

.LBB0_1119:
	s_or_b64 exec, exec, s[56:57]
	s_waitcnt lgkmcnt(1)
	v_fma_f32 v143, v185, v166, v183
	v_fmac_f32_e32 v143, v184, v167
	v_fmac_f32_e32 v143, v186, v154
	v_mul_f32_e32 v158, 0xbfb8aa3b, v143
	v_exp_f32_e32 v158, v158
	v_fma_f32 v159, v145, v160, v182
	v_fma_f32 v167, v185, v167, v183
	v_fmac_f32_e32 v167, v184, v154
	v_add_f32_e32 v158, 1.0, v158
	v_div_scale_f32 v160, s[0:1], v158, v158, v143
	v_rcp_f32_e32 v166, v160
	s_waitcnt lgkmcnt(0)
	v_div_scale_f32 v168, vcc, v143, v158, v143
	v_fmac_f32_e32 v167, v186, v155
	v_fma_f32 v169, -v160, v166, 1.0
	v_fmac_f32_e32 v166, v169, v166
	v_mul_f32_e32 v169, v168, v166
	v_fma_f32 v170, -v160, v169, v168
	v_fmac_f32_e32 v169, v170, v166
	v_fma_f32 v160, -v160, v169, v168
	v_mul_f32_e32 v168, 0xbfb8aa3b, v167
	v_exp_f32_e32 v168, v168
	v_fmac_f32_e32 v159, v141, v161
	v_div_fmas_f32 v160, v160, v166, v169
	v_fmac_f32_e32 v159, v181, v156
	v_div_fixup_f32 v143, v160, v158, v143
	v_add_f32_e32 v158, 1.0, v168
	v_mul_f32_e32 v143, v159, v143
	v_div_scale_f32 v159, s[0:1], v158, v158, v167
	v_rcp_f32_e32 v160, v159
	v_fma_f32 v161, v145, v161, v182
	v_fmac_f32_e32 v161, v141, v156
	v_fmac_f32_e32 v161, v181, v157
	v_fma_f32 v166, -v159, v160, 1.0
	v_fmac_f32_e32 v160, v166, v160
	v_div_scale_f32 v166, vcc, v167, v158, v167
	v_mul_f32_e32 v168, v166, v160
	v_fma_f32 v169, -v159, v168, v166
	v_fmac_f32_e32 v168, v169, v160
	v_fma_f32 v159, -v159, v168, v166
	v_div_fmas_f32 v159, v159, v160, v168
	v_div_fixup_f32 v158, v159, v158, v167
	v_mul_f32_e32 v158, v161, v158
	v_cvt_pk_bf16_f32 v143, v143, s0
	global_store_short v[162:163], v143, off offset:2080
	v_cvt_pk_bf16_f32 v143, v158, s0
	global_store_short v[164:165], v143, off offset:1056
	v_mov_b32_e32 v198, v208
	v_mov_b32_e32 v199, v209
	v_mov_b32_e32 v200, v210
	v_mov_b32_e32 v201, v211
	v_mov_b64_e32 v[170:171], s[46:47]
	ds_bpermute_b32 v152, v191, v152
	ds_bpermute_b32 v153, v191, v153
	ds_bpermute_b32 v164, v191, v150
	ds_bpermute_b32 v165, v191, v151
	v_pk_fma_f32 v[158:159], v[200:201], s[42:43], v[170:171] op_sel_hi:[1,0,0]
	s_nop 0
	v_mul_f32_e32 v143, 0x4b800000, v158
	v_mul_f32_e32 v160, 0x4b800000, v159
	v_cmp_gt_f32_e32 vcc, s91, v158
	v_cmp_gt_f32_e64 s[0:1], s91, v159
	v_pk_fma_f32 v[150:151], v[198:199], s[42:43], v[170:171] op_sel_hi:[1,0,0]
	v_cndmask_b32_e32 v143, v158, v143, vcc
	v_cndmask_b32_e64 v159, v159, v160, s[0:1]
	v_rsq_f32_e32 v158, v143
	v_rsq_f32_e32 v159, v159
	s_nop 0
	v_pk_mul_f32 v[160:161], v[158:159], s[44:45] op_sel_hi:[1,0]
	s_nop 0
	v_cndmask_b32_e64 v159, v159, v161, s[0:1]
	v_cndmask_b32_e32 v158, v158, v160, vcc
	v_pk_mul_f32 v[162:163], v[46:47], v[158:159]
	v_pk_mul_f32 v[160:161], v[38:39], v[158:159]
	ds_bpermute_b32 v168, v191, v162
	ds_bpermute_b32 v167, v191, v163
	ds_bpermute_b32 v166, v191, v160
	ds_bpermute_b32 v143, v191, v161
	v_cmp_gt_f32_e32 vcc, s91, v151
	v_cmp_gt_f32_e64 s[0:1], s91, v150
	s_and_saveexec_b64 s[56:57], s[8:9]
	s_cbranch_execz .LBB0_1121
	s_waitcnt lgkmcnt(0)
	v_mov_b32_e32 v143, v165
	v_mov_b32_e32 v166, v164
	v_mov_b32_e32 v167, v153
	v_mov_b32_e32 v168, v152

.LBB0_1123:
	s_or_b64 exec, exec, s[0:1]
	s_waitcnt lgkmcnt(0)
	v_pk_mul_f32 v[156:157], v[40:41], v[164:165]
	v_fma_f32 v206, v185, v171, v183
	v_fma_f32 v198, v185, v156, v183
	v_fmac_f32_e32 v198, v184, v157
	v_fmac_f32_e32 v198, v186, v150
	v_mul_f32_e32 v199, 0xbfb8aa3b, v198
	v_exp_f32_e32 v199, v199
	v_fmac_f32_e32 v206, v184, v156
	v_fmac_f32_e32 v206, v186, v157
	v_pk_mul_f32 v[164:165], v[32:33], v[164:165]
	v_add_f32_e32 v199, 1.0, v199
	v_div_scale_f32 v200, s[0:1], v199, v199, v198
	v_rcp_f32_e32 v201, v200
	v_fma_f32 v202, v145, v164, v182
	v_fma_f32 v197, v185, v197, v183
	v_fmac_f32_e32 v202, v141, v165
	v_fma_f32 v203, -v200, v201, 1.0
	v_fmac_f32_e32 v201, v203, v201
	v_div_scale_f32 v203, vcc, v198, v199, v198
	v_mul_f32_e32 v204, v203, v201
	v_fma_f32 v205, -v200, v204, v203
	v_fmac_f32_e32 v204, v205, v201
	v_fma_f32 v200, -v200, v204, v203
	v_fma_f32 v203, v185, v157, v183
	v_fmac_f32_e32 v203, v184, v150
	v_fmac_f32_e32 v203, v186, v151
	v_mul_f32_e32 v205, 0xbfb8aa3b, v203
	v_exp_f32_e32 v205, v205
	v_div_fmas_f32 v200, v200, v201, v204
	v_div_fixup_f32 v198, v200, v199, v198
	v_mul_f32_e32 v157, 0xbfb8aa3b, v206
	v_add_f32_e32 v199, 1.0, v205
	v_div_scale_f32 v200, s[0:1], v199, v199, v203
	v_rcp_f32_e32 v201, v200
	v_exp_f32_e32 v157, v157
	v_fmac_f32_e32 v197, v184, v171
	v_fmac_f32_e32 v202, v181, v158
	v_fma_f32 v204, -v200, v201, 1.0
	v_fmac_f32_e32 v201, v204, v201
	v_div_scale_f32 v204, vcc, v203, v199, v203
	v_mul_f32_e32 v205, v204, v201
	v_fma_f32 v207, -v200, v205, v204
	v_fmac_f32_e32 v205, v207, v201
	v_add_f32_e32 v157, 1.0, v157
	v_fma_f32 v200, -v200, v205, v204
	v_div_scale_f32 v204, s[0:1], v157, v157, v206
	v_rcp_f32_e32 v207, v204
	v_div_fmas_f32 v200, v200, v201, v205
	v_fmac_f32_e32 v197, v186, v156
	v_mul_f32_e32 v198, v202, v198
	v_fma_f32 v202, v145, v165, v182
	v_div_fixup_f32 v199, v200, v199, v203
	v_fma_f32 v200, -v204, v207, 1.0
	v_mul_f32_e32 v156, 0xbfb8aa3b, v197
	v_fmac_f32_e32 v202, v141, v158
	v_fmac_f32_e32 v207, v200, v207
	v_div_scale_f32 v200, vcc, v206, v157, v206
	v_exp_f32_e32 v156, v156
	v_fmac_f32_e32 v202, v181, v159
	v_mul_f32_e32 v201, v200, v207
	v_mul_f32_e32 v199, v202, v199
	v_fma_f32 v202, -v204, v201, v200
	v_fmac_f32_e32 v201, v202, v207
	v_fma_f32 v200, -v204, v201, v200
	v_add_f32_e32 v156, 1.0, v156
	v_div_fmas_f32 v171, v200, v207, v201
	v_div_scale_f32 v200, s[0:1], v156, v156, v197
	v_rcp_f32_e32 v201, v200
	v_div_fixup_f32 v157, v171, v157, v206
	v_fma_f32 v171, v145, v143, v182
	v_fmac_f32_e32 v171, v141, v164
	v_fmac_f32_e32 v171, v181, v165
	v_fma_f32 v165, -v200, v201, 1.0
	v_fmac_f32_e32 v201, v165, v201
	v_div_scale_f32 v165, vcc, v197, v156, v197
	v_mul_f32_e32 v157, v171, v157
	v_mul_f32_e32 v171, v165, v201
	v_fma_f32 v202, -v200, v171, v165
	v_fmac_f32_e32 v171, v202, v201
	v_fma_f32 v165, -v200, v171, v165
	v_div_fmas_f32 v165, v165, v201, v171
	v_div_fixup_f32 v156, v165, v156, v197
	v_fma_f32 v165, v145, v170, v182
	v_fmac_f32_e32 v165, v141, v143
	v_fmac_f32_e32 v165, v181, v164
	v_mul_f32_e32 v143, v165, v156
	v_cvt_pk_bf16_f32 v143, v143, s0
	global_store_short v[152:153], v143, off offset:32
	v_cvt_pk_bf16_f32 v143, v157, s0
	global_store_short v[166:167], v143, off offset:3104
	v_cvt_pk_bf16_f32 v143, v198, s0
	global_store_short v[168:169], v143, off offset:2080
	v_cvt_pk_bf16_f32 v143, v199, s0
	global_store_short v[154:155], v143, off offset:1056
	v_mov_b32_e32 v154, v212
	v_mov_b32_e32 v155, v213
	v_mov_b32_e32 v156, v214
	v_mov_b32_e32 v157, v215
	v_mov_b64_e32 v[166:167], s[46:47]
	ds_bpermute_b32 v162, v191, v162
	ds_bpermute_b32 v163, v191, v163
	ds_bpermute_b32 v160, v191, v160
	ds_bpermute_b32 v161, v191, v161
	v_pk_fma_f32 v[152:153], v[156:157], s[42:43], v[166:167] op_sel_hi:[1,0,0]
	s_nop 0
	v_mul_f32_e32 v143, 0x4b800000, v152
	v_cmp_gt_f32_e32 vcc, s91, v152
	v_cmp_gt_f32_e64 s[0:1], s91, v153
	v_pk_fma_f32 v[154:155], v[154:155], s[42:43], v[166:167] op_sel_hi:[1,0,0]
	v_cndmask_b32_e32 v143, v152, v143, vcc
	v_rsq_f32_e32 v152, v143
	v_mul_f32_e32 v143, 0x4b800000, v153
	v_cndmask_b32_e64 v143, v153, v143, s[0:1]
	v_rsq_f32_e32 v153, v143
	s_nop 0
	v_pk_mul_f32 v[156:157], v[152:153], s[44:45] op_sel_hi:[1,0]
	s_nop 0
	v_cndmask_b32_e64 v165, v153, v157, s[0:1]
	v_cndmask_b32_e32 v164, v152, v156, vcc
	v_pk_mul_f32 v[152:153], v[30:31], v[164:165]
	v_pk_mul_f32 v[156:157], v[22:23], v[164:165]
	ds_bpermute_b32 v170, v191, v152
	ds_bpermute_b32 v169, v191, v153
	ds_bpermute_b32 v168, v191, v156
	ds_bpermute_b32 v143, v191, v157
	v_cmp_gt_f32_e32 vcc, s91, v155
	v_cmp_gt_f32_e64 s[0:1], s91, v154
	s_and_saveexec_b64 s[56:57], s[8:9]
	s_cbranch_execz .LBB0_1125
	s_waitcnt lgkmcnt(0)
	v_mov_b32_e32 v143, v161
	v_mov_b32_e32 v168, v160
	v_mov_b32_e32 v169, v163
	v_mov_b32_e32 v170, v162

.LBB0_1127:
	s_or_b64 exec, exec, s[0:1]
	s_waitcnt lgkmcnt(0)
	v_pk_mul_f32 v[158:159], v[24:25], v[166:167]
	v_fma_f32 v206, v185, v165, v183
	v_fma_f32 v198, v185, v158, v183
	v_fmac_f32_e32 v198, v184, v159
	v_fmac_f32_e32 v198, v186, v154
	v_mul_f32_e32 v199, 0xbfb8aa3b, v198
	v_exp_f32_e32 v199, v199
	v_fmac_f32_e32 v206, v184, v158
	v_fmac_f32_e32 v206, v186, v159
	v_pk_mul_f32 v[166:167], v[16:17], v[166:167]
	v_add_f32_e32 v199, 1.0, v199
	v_div_scale_f32 v200, s[0:1], v199, v199, v198
	v_rcp_f32_e32 v201, v200
	v_fma_f32 v202, v145, v166, v182
	v_fma_f32 v197, v185, v197, v183
	v_fmac_f32_e32 v202, v141, v167
	v_fma_f32 v203, -v200, v201, 1.0
	v_fmac_f32_e32 v201, v203, v201
	v_div_scale_f32 v203, vcc, v198, v199, v198
	v_mul_f32_e32 v204, v203, v201
	v_fma_f32 v205, -v200, v204, v203
	v_fmac_f32_e32 v204, v205, v201
	v_fma_f32 v200, -v200, v204, v203
	v_fma_f32 v203, v185, v159, v183
	v_fmac_f32_e32 v203, v184, v154
	v_fmac_f32_e32 v203, v186, v155
	v_mul_f32_e32 v205, 0xbfb8aa3b, v203
	v_exp_f32_e32 v205, v205
	v_div_fmas_f32 v200, v200, v201, v204
	v_div_fixup_f32 v198, v200, v199, v198
	v_mul_f32_e32 v159, 0xbfb8aa3b, v206
	v_add_f32_e32 v199, 1.0, v205
	v_div_scale_f32 v200, s[0:1], v199, v199, v203
	v_rcp_f32_e32 v201, v200
	v_exp_f32_e32 v159, v159
	v_fmac_f32_e32 v197, v184, v165
	v_fmac_f32_e32 v202, v181, v160
	v_fma_f32 v204, -v200, v201, 1.0
	v_fmac_f32_e32 v201, v204, v201
	v_div_scale_f32 v204, vcc, v203, v199, v203
	v_mul_f32_e32 v205, v204, v201
	v_fma_f32 v207, -v200, v205, v204
	v_fmac_f32_e32 v205, v207, v201
	v_add_f32_e32 v159, 1.0, v159
	v_fma_f32 v200, -v200, v205, v204
	v_div_scale_f32 v204, s[0:1], v159, v159, v206
	v_rcp_f32_e32 v207, v204
	v_div_fmas_f32 v200, v200, v201, v205
	v_fmac_f32_e32 v197, v186, v158
	v_mul_f32_e32 v198, v202, v198
	v_fma_f32 v202, v145, v167, v182
	v_div_fixup_f32 v199, v200, v199, v203
	v_fma_f32 v200, -v204, v207, 1.0
	v_mul_f32_e32 v158, 0xbfb8aa3b, v197
	v_fmac_f32_e32 v202, v141, v160
	v_fmac_f32_e32 v207, v200, v207
	v_div_scale_f32 v200, vcc, v206, v159, v206
	v_exp_f32_e32 v158, v158
	v_fmac_f32_e32 v202, v181, v161
	v_mul_f32_e32 v201, v200, v207
	v_mul_f32_e32 v199, v202, v199
	v_fma_f32 v202, -v204, v201, v200
	v_fmac_f32_e32 v201, v202, v207
	v_fma_f32 v200, -v204, v201, v200
	v_add_f32_e32 v158, 1.0, v158
	v_div_fmas_f32 v165, v200, v207, v201
	v_div_scale_f32 v200, s[0:1], v158, v158, v197
	v_rcp_f32_e32 v201, v200
	v_div_fixup_f32 v159, v165, v159, v206
	v_fma_f32 v165, v145, v143, v182
	v_fmac_f32_e32 v165, v141, v166
	v_fmac_f32_e32 v165, v181, v167
	v_mul_f32_e32 v159, v165, v159
	v_fma_f32 v165, -v200, v201, 1.0
	v_fmac_f32_e32 v201, v165, v201
	v_div_scale_f32 v165, vcc, v197, v158, v197
	v_mul_f32_e32 v167, v165, v201
	v_fma_f32 v202, -v200, v167, v165
	v_fmac_f32_e32 v167, v202, v201
	v_fma_f32 v165, -v200, v167, v165
	v_fma_f32 v164, v145, v164, v182
	v_div_fmas_f32 v165, v165, v201, v167
	v_fmac_f32_e32 v164, v141, v143
	v_div_fixup_f32 v158, v165, v158, v197
	v_fmac_f32_e32 v164, v181, v166
	v_mul_f32_e32 v143, v164, v158
	v_cvt_pk_bf16_f32 v143, v143, s0
	global_store_short v[162:163], v143, off offset:32
	v_cvt_pk_bf16_f32 v143, v159, s0
	global_store_short v[168:169], v143, off offset:3104
	v_cvt_pk_bf16_f32 v143, v198, s0
	global_store_short v[170:171], v143, off offset:2080
	v_cvt_pk_bf16_f32 v143, v199, s0
	global_store_short v[150:151], v143, off offset:1056
	v_mov_b32_e32 v198, v216
	v_mov_b32_e32 v199, v217
	v_mov_b32_e32 v200, v218
	v_mov_b32_e32 v201, v219
	v_mov_b64_e32 v[150:151], s[46:47]
	ds_bpermute_b32 v152, v191, v152
	ds_bpermute_b32 v153, v191, v153
	ds_bpermute_b32 v156, v191, v156
	ds_bpermute_b32 v157, v191, v157
	v_pk_fma_f32 v[158:159], v[200:201], s[42:43], v[150:151] op_sel_hi:[1,0,0]
	s_nop 0
	v_mul_f32_e32 v143, 0x4b800000, v158
	v_cmp_gt_f32_e32 vcc, s91, v158
	v_cmp_gt_f32_e64 s[0:1], s91, v159
	v_pk_fma_f32 v[150:151], v[198:199], s[42:43], v[150:151] op_sel_hi:[1,0,0]
	v_cndmask_b32_e32 v143, v158, v143, vcc
	v_rsq_f32_e32 v158, v143
	v_mul_f32_e32 v143, 0x4b800000, v159
	v_cndmask_b32_e64 v143, v159, v143, s[0:1]
	v_rsq_f32_e32 v159, v143
	s_nop 0
	v_pk_mul_f32 v[162:163], v[158:159], s[44:45] op_sel_hi:[1,0]
	s_nop 0
	v_cndmask_b32_e64 v159, v159, v163, s[0:1]
	v_cndmask_b32_e32 v158, v158, v162, vcc
	v_pk_mul_f32 v[164:165], v[14:15], v[158:159]
	v_pk_mul_f32 v[162:163], v[6:7], v[158:159]
	ds_bpermute_b32 v168, v191, v164
	ds_bpermute_b32 v167, v191, v165
	ds_bpermute_b32 v166, v191, v162
	ds_bpermute_b32 v143, v191, v163
	v_cmp_gt_f32_e32 vcc, s91, v151
	v_cmp_gt_f32_e64 s[0:1], s91, v150
	s_and_saveexec_b64 s[56:57], s[8:9]
	s_cbranch_execz .LBB0_1129
	s_waitcnt lgkmcnt(0)
	v_mov_b32_e32 v143, v157
	v_mov_b32_e32 v166, v156
	v_mov_b32_e32 v167, v153
	v_mov_b32_e32 v168, v152

.LBB0_1131:
	s_or_b64 exec, exec, s[0:1]
	s_waitcnt lgkmcnt(6)
	v_pk_mul_f32 v[160:161], v[8:9], v[152:153]
	v_pk_mul_f32 v[152:153], v[0:1], v[152:153]
	s_waitcnt lgkmcnt(1)
	v_fma_f32 v169, v185, v160, v183
	v_fmac_f32_e32 v169, v184, v161
	v_fmac_f32_e32 v169, v186, v164
	s_waitcnt lgkmcnt(0)
	v_mul_f32_e32 v170, 0xbfb8aa3b, v169
	v_exp_f32_e32 v170, v170
	v_fma_f32 v198, v145, v152, v182
	v_fmac_f32_e32 v198, v141, v153
	v_fmac_f32_e32 v198, v181, v158
	v_add_f32_e32 v170, 1.0, v170
	v_div_scale_f32 v171, s[0:1], v170, v170, v169
	v_rcp_f32_e32 v197, v171
	v_fma_f32 v168, v185, v168, v183
	v_fmac_f32_e32 v168, v184, v167
	v_fmac_f32_e32 v168, v186, v160
	v_fma_f32 v199, -v171, v197, 1.0
	v_fmac_f32_e32 v197, v199, v197
	v_div_scale_f32 v199, vcc, v169, v170, v169
	v_mul_f32_e32 v200, v199, v197
	v_fma_f32 v201, -v171, v200, v199
	v_fmac_f32_e32 v200, v201, v197
	v_fma_f32 v171, -v171, v200, v199
	v_fma_f32 v199, v185, v161, v183
	v_fmac_f32_e32 v199, v184, v164
	v_fmac_f32_e32 v199, v186, v165
	v_mul_f32_e32 v164, 0xbfb8aa3b, v199
	v_exp_f32_e32 v164, v164
	v_div_fmas_f32 v165, v171, v197, v200
	v_div_fixup_f32 v165, v165, v170, v169
	v_fma_f32 v197, v185, v167, v183
	v_add_f32_e32 v164, 1.0, v164
	v_div_scale_f32 v169, s[0:1], v164, v164, v199
	v_rcp_f32_e32 v170, v169
	v_fmac_f32_e32 v197, v184, v160
	v_fmac_f32_e32 v197, v186, v161
	v_fma_f32 v171, v145, v153, v182
	v_mul_f32_e32 v161, 0xbfb8aa3b, v197
	v_fmac_f32_e32 v171, v141, v158
	v_fma_f32 v158, -v169, v170, 1.0
	v_exp_f32_e32 v161, v161
	v_fmac_f32_e32 v170, v158, v170
	v_div_scale_f32 v158, vcc, v199, v164, v199
	v_fmac_f32_e32 v171, v181, v159
	v_mul_f32_e32 v159, v158, v170
	v_mul_f32_e32 v165, v198, v165
	v_fma_f32 v198, -v169, v159, v158
	v_fmac_f32_e32 v159, v198, v170
	v_add_f32_e32 v161, 1.0, v161
	v_fma_f32 v158, -v169, v159, v158
	v_div_scale_f32 v169, s[0:1], v161, v161, v197
	v_rcp_f32_e32 v198, v169
	v_div_fmas_f32 v158, v158, v170, v159
	v_mul_f32_e32 v160, 0xbfb8aa3b, v168
	v_exp_f32_e32 v160, v160
	v_fma_f32 v159, -v169, v198, 1.0
	v_fmac_f32_e32 v198, v159, v198
	v_div_scale_f32 v159, vcc, v197, v161, v197
	v_div_fixup_f32 v158, v158, v164, v199
	v_mul_f32_e32 v164, v159, v198
	v_fma_f32 v170, -v169, v164, v159
	v_fmac_f32_e32 v164, v170, v198
	v_fma_f32 v159, -v169, v164, v159
	v_add_f32_e32 v160, 1.0, v160
	v_div_fmas_f32 v159, v159, v198, v164
	v_div_scale_f32 v164, s[0:1], v160, v160, v168
	v_rcp_f32_e32 v167, v164
	v_div_fixup_f32 v159, v159, v161, v197
	v_fma_f32 v161, v145, v143, v182
	v_fmac_f32_e32 v161, v141, v152
	v_fmac_f32_e32 v161, v181, v153
	v_mul_f32_e32 v153, v161, v159
	v_fma_f32 v159, -v164, v167, 1.0
	v_fmac_f32_e32 v167, v159, v167
	v_div_scale_f32 v159, vcc, v168, v160, v168
	v_mul_f32_e32 v161, v159, v167
	v_fma_f32 v169, -v164, v161, v159
	v_fmac_f32_e32 v161, v169, v167
	v_fma_f32 v159, -v164, v161, v159
	v_div_fmas_f32 v159, v159, v167, v161
	v_div_fixup_f32 v159, v159, v160, v168
	v_fma_f32 v160, v145, v166, v182
	v_fmac_f32_e32 v160, v141, v143
	v_fmac_f32_e32 v160, v181, v152
	v_mul_f32_e32 v143, v160, v159
	v_cvt_pk_bf16_f32 v143, v143, s0
	global_store_short v[150:151], v143, off offset:32
	v_cvt_pk_bf16_f32 v143, v153, s0
	v_mul_f32_e32 v158, v171, v158
	global_store_short v[156:157], v143, off offset:3104
	v_cvt_pk_bf16_f32 v143, v165, s0
	global_store_short v[162:163], v143, off offset:2080
	v_cvt_pk_bf16_f32 v143, v158, s0
	global_store_short v[154:155], v143, off offset:1056
	v_mov_b32_e32 v150, v220
	v_mov_b32_e32 v151, v221
	v_mov_b32_e32 v152, v222
	v_mov_b32_e32 v153, v223
	v_mov_b64_e32 v[158:159], s[46:47]
	v_pk_fma_f32 v[152:153], v[152:153], s[42:43], v[158:159] op_sel_hi:[1,0,0]
	s_nop 0
	v_mul_f32_e32 v143, 0x4b800000, v152
	v_cmp_gt_f32_e32 vcc, s91, v152
	v_cmp_gt_f32_e64 s[0:1], s91, v153
	v_pk_fma_f32 v[150:151], v[150:151], s[42:43], v[158:159] op_sel_hi:[1,0,0]
	v_cndmask_b32_e32 v143, v152, v143, vcc
	v_rsq_f32_e32 v152, v143
	v_mul_f32_e32 v143, 0x4b800000, v153
	v_cndmask_b32_e64 v143, v153, v143, s[0:1]
	v_rsq_f32_e32 v153, v143
	v_add_u32_e32 v143, s84, v196
	v_pk_mul_f32 v[154:155], v[152:153], s[44:45] op_sel_hi:[1,0]
	s_nop 0
	v_cndmask_b32_e64 v153, v153, v155, s[0:1]
	v_cndmask_b32_e32 v152, v152, v154, vcc
	v_pk_mul_f32 v[126:127], v[126:127], v[152:153]
	v_pk_mul_f32 v[122:123], v[122:123], v[152:153]
	ds_bpermute_b32 v156, v191, v126
	ds_bpermute_b32 v154, v191, v127
	ds_bpermute_b32 v157, v191, v122
	ds_bpermute_b32 v155, v191, v123
	v_cmp_gt_f32_e32 vcc, s91, v151
	v_cmp_gt_f32_e64 s[0:1], s91, v150
	s_and_saveexec_b64 s[56:57], s[8:9]
	s_cbranch_execz .LBB0_1133
	s_waitcnt lgkmcnt(0)
	ds_read2_b32 v[154:155], v143 offset0:64 offset1:96
	ds_read2_b32 v[156:157], v143 offset1:32

.LBB0_1135:
	s_or_b64 exec, exec, s[0:1]
	v_pk_mul_f32 v[116:117], v[116:117], v[150:151]
	v_pk_mul_f32 v[112:113], v[112:113], v[150:151]
	v_fma_f32 v143, v185, v116, v183
	v_fmac_f32_e32 v143, v184, v117
	v_fmac_f32_e32 v143, v186, v118
	v_mul_f32_e32 v160, 0xbfb8aa3b, v143
	v_exp_f32_e32 v160, v160
	s_waitcnt lgkmcnt(1)
	v_fma_f32 v165, v185, v152, v183
	v_fmac_f32_e32 v165, v184, v116
	v_fmac_f32_e32 v165, v186, v117
	v_add_f32_e32 v150, 1.0, v160
	v_div_scale_f32 v151, s[0:1], v150, v150, v143
	v_rcp_f32_e32 v160, v151
	s_waitcnt lgkmcnt(0)
	v_fma_f32 v158, v185, v158, v183
	v_fma_f32 v161, v145, v112, v182
	v_fmac_f32_e32 v158, v184, v152
	v_fma_f32 v162, -v151, v160, 1.0
	v_fmac_f32_e32 v160, v162, v160
	v_div_scale_f32 v162, vcc, v143, v150, v143
	v_mul_f32_e32 v163, v162, v160
	v_fma_f32 v164, -v151, v163, v162
	v_fmac_f32_e32 v163, v164, v160
	v_fma_f32 v151, -v151, v163, v162
	v_fma_f32 v162, v185, v117, v183
	v_fmac_f32_e32 v162, v184, v118
	v_fmac_f32_e32 v162, v186, v119
	v_mul_f32_e32 v164, 0xbfb8aa3b, v162
	v_exp_f32_e32 v164, v164
	v_div_fmas_f32 v151, v151, v160, v163
	v_div_fixup_f32 v143, v151, v150, v143
	v_mul_f32_e32 v117, 0xbfb8aa3b, v165
	v_add_f32_e32 v150, 1.0, v164
	v_div_scale_f32 v151, s[0:1], v150, v150, v162
	v_rcp_f32_e32 v160, v151
	v_exp_f32_e32 v117, v117
	v_fmac_f32_e32 v161, v141, v113
	v_fmac_f32_e32 v158, v186, v116
	v_fma_f32 v163, -v151, v160, 1.0
	v_fmac_f32_e32 v160, v163, v160
	v_div_scale_f32 v163, vcc, v162, v150, v162
	v_mul_f32_e32 v164, v163, v160
	v_fma_f32 v166, -v151, v164, v163
	v_fmac_f32_e32 v164, v166, v160
	v_add_f32_e32 v117, 1.0, v117
	v_fma_f32 v151, -v151, v164, v163
	v_div_scale_f32 v163, s[0:1], v117, v117, v165
	v_rcp_f32_e32 v166, v163
	v_fmac_f32_e32 v161, v181, v114
	v_div_fmas_f32 v151, v151, v160, v164
	v_mul_f32_e32 v116, 0xbfb8aa3b, v158
	v_mul_f32_e32 v143, v161, v143
	v_fma_f32 v161, v145, v113, v182
	v_div_fixup_f32 v150, v151, v150, v162
	v_fma_f32 v151, -v163, v166, 1.0
	v_exp_f32_e32 v116, v116
	v_fmac_f32_e32 v161, v141, v114
	v_fmac_f32_e32 v166, v151, v166
	v_div_scale_f32 v151, vcc, v165, v117, v165
	v_fmac_f32_e32 v161, v181, v115
	v_mul_f32_e32 v160, v151, v166
	v_mul_f32_e32 v150, v161, v150
	v_fma_f32 v161, -v163, v160, v151
	v_fmac_f32_e32 v160, v161, v166
	v_add_f32_e32 v116, 1.0, v116
	v_fma_f32 v151, -v163, v160, v151
	v_div_scale_f32 v152, s[0:1], v116, v116, v158
	v_div_fmas_f32 v151, v151, v166, v160
	v_rcp_f32_e32 v160, v152
	v_div_fixup_f32 v117, v151, v117, v165
	v_fma_f32 v151, v145, v153, v182
	v_fmac_f32_e32 v151, v141, v112
	v_fmac_f32_e32 v151, v181, v113
	v_mul_f32_e32 v113, v151, v117
	v_fma_f32 v117, -v152, v160, 1.0
	v_fmac_f32_e32 v160, v117, v160
	v_div_scale_f32 v117, vcc, v158, v116, v158
	v_mul_f32_e32 v151, v117, v160
	v_fma_f32 v161, -v152, v151, v117
	v_fmac_f32_e32 v151, v161, v160
	v_fma_f32 v117, -v152, v151, v117
	v_div_fmas_f32 v117, v117, v160, v151
	v_div_fixup_f32 v116, v117, v116, v158
	v_fma_f32 v117, v145, v159, v182
	v_fmac_f32_e32 v117, v141, v153
	v_fmac_f32_e32 v117, v181, v112
	v_mul_f32_e32 v112, v117, v116
	v_cvt_pk_bf16_f32 v112, v112, s0
	global_store_short v[120:121], v112, off offset:32
	v_cvt_pk_bf16_f32 v112, v113, s0
	global_store_short v[124:125], v112, off offset:3104
	v_cvt_pk_bf16_f32 v112, v143, s0
	global_store_short v[154:155], v112, off offset:2080
	v_cvt_pk_bf16_f32 v112, v150, s0
	global_store_short v[156:157], v112, off offset:1056
	v_mov_b32_e32 v152, v224
	v_mov_b32_e32 v153, v225
	v_mov_b32_e32 v154, v226
	v_mov_b32_e32 v155, v227
	v_mov_b64_e32 v[112:113], s[46:47]
	ds_bpermute_b32 v122, v191, v122
	ds_bpermute_b32 v123, v191, v123
	v_pk_fma_f32 v[116:117], v[154:155], s[42:43], v[112:113] op_sel_hi:[1,0,0]
	s_nop 0
	v_mul_f32_e32 v120, 0x4b800000, v116
	v_cmp_gt_f32_e32 vcc, s91, v116
	v_cmp_gt_f32_e64 s[0:1], s91, v117
	v_pk_fma_f32 v[112:113], v[152:153], s[42:43], v[112:113] op_sel_hi:[1,0,0]
	v_cndmask_b32_e32 v116, v116, v120, vcc
	v_mul_f32_e32 v120, 0x4b800000, v117
	v_cndmask_b32_e64 v117, v117, v120, s[0:1]
	v_rsq_f32_e32 v116, v116
	v_rsq_f32_e32 v117, v117
	s_nop 0
	v_pk_mul_f32 v[120:121], v[116:117], s[44:45] op_sel_hi:[1,0]
	s_nop 0
	v_cndmask_b32_e64 v117, v117, v121, s[0:1]
	v_cndmask_b32_e32 v116, v116, v120, vcc
	v_pk_mul_f32 v[110:111], v[110:111], v[116:117]
	v_pk_mul_f32 v[106:107], v[106:107], v[116:117]
	ds_bpermute_b32 v150, v191, v110
	ds_bpermute_b32 v143, v191, v111
	ds_bpermute_b32 v125, v191, v106
	ds_bpermute_b32 v124, v191, v107
	ds_bpermute_b32 v120, v191, v126
	ds_bpermute_b32 v121, v191, v127
	v_cmp_gt_f32_e32 vcc, s91, v113
	v_cmp_gt_f32_e64 s[0:1], s91, v112
	s_and_saveexec_b64 s[56:57], s[8:9]
	s_cbranch_execz .LBB0_1137
	s_waitcnt lgkmcnt(2)
	v_mov_b32_e32 v124, v123
	v_mov_b32_e32 v125, v122
	s_waitcnt lgkmcnt(0)
	v_mov_b32_e32 v143, v121
	v_mov_b32_e32 v150, v120

.LBB0_1139:
	s_or_b64 exec, exec, s[0:1]
	v_pk_mul_f32 v[100:101], v[100:101], v[112:113]
	v_pk_mul_f32 v[96:97], v[96:97], v[112:113]
	s_waitcnt lgkmcnt(3)
	v_fma_f32 v114, v185, v100, v183
	v_fmac_f32_e32 v114, v184, v101
	v_fmac_f32_e32 v114, v186, v102
	s_waitcnt lgkmcnt(2)
	v_mul_f32_e32 v115, 0xbfb8aa3b, v114
	v_exp_f32_e32 v115, v115
	s_waitcnt lgkmcnt(0)
	v_fma_f32 v143, v185, v124, v183
	v_fmac_f32_e32 v143, v184, v100
	v_fmac_f32_e32 v143, v186, v101
	v_add_f32_e32 v112, 1.0, v115
	v_div_scale_f32 v113, s[0:1], v112, v112, v114
	v_rcp_f32_e32 v115, v113
	v_fma_f32 v118, v145, v96, v182
	v_fmac_f32_e32 v118, v141, v97
	v_fmac_f32_e32 v118, v181, v98
	v_fma_f32 v119, -v113, v115, 1.0
	v_fmac_f32_e32 v115, v119, v115
	v_div_scale_f32 v119, vcc, v114, v112, v114
	v_mul_f32_e32 v126, v119, v115
	v_fma_f32 v127, -v113, v126, v119
	v_fmac_f32_e32 v126, v127, v115
	v_fma_f32 v113, -v113, v126, v119
	v_fma_f32 v119, v185, v101, v183
	v_fmac_f32_e32 v119, v184, v102
	v_fmac_f32_e32 v119, v186, v103
	v_mul_f32_e32 v127, 0xbfb8aa3b, v119
	v_exp_f32_e32 v127, v127
	v_div_fmas_f32 v113, v113, v115, v126
	v_div_fixup_f32 v112, v113, v112, v114
	v_mul_f32_e32 v101, 0xbfb8aa3b, v143
	v_add_f32_e32 v113, 1.0, v127
	v_div_scale_f32 v114, s[0:1], v113, v113, v119
	v_rcp_f32_e32 v115, v114
	v_exp_f32_e32 v101, v101
	v_mul_f32_e32 v112, v118, v112
	v_fma_f32 v118, v145, v97, v182
	v_fma_f32 v126, -v114, v115, 1.0
	v_fmac_f32_e32 v115, v126, v115
	v_div_scale_f32 v126, vcc, v119, v113, v119
	v_mul_f32_e32 v127, v126, v115
	v_fma_f32 v150, -v114, v127, v126
	v_fmac_f32_e32 v127, v150, v115
	v_add_f32_e32 v101, 1.0, v101
	v_fma_f32 v114, -v114, v127, v126
	v_div_scale_f32 v126, s[0:1], v101, v101, v143
	v_rcp_f32_e32 v150, v126
	v_div_fmas_f32 v114, v114, v115, v127
	v_div_fixup_f32 v113, v114, v113, v119
	v_fmac_f32_e32 v118, v141, v98
	v_fma_f32 v114, -v126, v150, 1.0
	v_fmac_f32_e32 v150, v114, v150
	v_div_scale_f32 v114, vcc, v143, v101, v143
	v_fmac_f32_e32 v118, v181, v99
	v_mul_f32_e32 v115, v114, v150
	v_mul_f32_e32 v113, v118, v113
	v_fma_f32 v118, -v126, v115, v114
	v_fmac_f32_e32 v115, v118, v150
	v_fma_f32 v118, v185, v125, v183
	v_fmac_f32_e32 v118, v184, v124
	v_fmac_f32_e32 v118, v186, v100
	v_mul_f32_e32 v100, 0xbfb8aa3b, v118
	v_exp_f32_e32 v100, v100
	v_fma_f32 v114, -v126, v115, v114
	v_div_fmas_f32 v114, v114, v150, v115
	v_div_fixup_f32 v101, v114, v101, v143
	v_add_f32_e32 v100, 1.0, v100
	v_div_scale_f32 v115, s[0:1], v100, v100, v118
	v_rcp_f32_e32 v119, v115
	v_fma_f32 v114, v145, v116, v182
	v_fmac_f32_e32 v114, v141, v96
	v_fmac_f32_e32 v114, v181, v97
	v_mul_f32_e32 v97, v114, v101
	v_fma_f32 v101, -v115, v119, 1.0
	v_fmac_f32_e32 v119, v101, v119
	v_div_scale_f32 v101, vcc, v118, v100, v118
	v_mul_f32_e32 v114, v101, v119
	v_fma_f32 v124, -v115, v114, v101
	v_fmac_f32_e32 v114, v124, v119
	v_fma_f32 v101, -v115, v114, v101
	v_div_fmas_f32 v101, v101, v119, v114
	v_div_fixup_f32 v100, v101, v100, v118
	v_fma_f32 v101, v145, v117, v182
	v_fmac_f32_e32 v101, v141, v116
	v_fmac_f32_e32 v101, v181, v96
	v_mul_f32_e32 v96, v101, v100
	v_cvt_pk_bf16_f32 v96, v96, s0
	global_store_short v[104:105], v96, off offset:32
	v_cvt_pk_bf16_f32 v96, v97, s0
	global_store_short v[108:109], v96, off offset:3104
	v_cvt_pk_bf16_f32 v96, v112, s0
	global_store_short v[120:121], v96, off offset:2080
	v_cvt_pk_bf16_f32 v96, v113, s0
	global_store_short v[122:123], v96, off offset:1056
	v_mov_b32_e32 v114, v228
	v_mov_b32_e32 v115, v229
	v_mov_b32_e32 v116, v230
	v_mov_b32_e32 v117, v231
	v_mov_b64_e32 v[96:97], s[46:47]
	ds_bpermute_b32 v106, v191, v106
	ds_bpermute_b32 v107, v191, v107
	v_pk_fma_f32 v[100:101], v[116:117], s[42:43], v[96:97] op_sel_hi:[1,0,0]
	s_nop 0
	v_mul_f32_e32 v104, 0x4b800000, v100
	v_cmp_gt_f32_e32 vcc, s91, v100
	v_cmp_gt_f32_e64 s[0:1], s91, v101
	v_pk_fma_f32 v[96:97], v[114:115], s[42:43], v[96:97] op_sel_hi:[1,0,0]
	v_cndmask_b32_e32 v100, v100, v104, vcc
	v_mul_f32_e32 v104, 0x4b800000, v101
	v_cndmask_b32_e64 v101, v101, v104, s[0:1]
	v_rsq_f32_e32 v100, v100
	v_rsq_f32_e32 v101, v101
	s_nop 0
	v_pk_mul_f32 v[104:105], v[100:101], s[44:45] op_sel_hi:[1,0]
	s_nop 0
	v_cndmask_b32_e64 v101, v101, v105, s[0:1]
	v_cndmask_b32_e32 v100, v100, v104, vcc
	v_pk_mul_f32 v[94:95], v[94:95], v[100:101]
	v_pk_mul_f32 v[90:91], v[90:91], v[100:101]
	ds_bpermute_b32 v113, v191, v94
	ds_bpermute_b32 v112, v191, v95
	ds_bpermute_b32 v109, v191, v90
	ds_bpermute_b32 v108, v191, v91
	ds_bpermute_b32 v104, v191, v110
	ds_bpermute_b32 v105, v191, v111
	v_cmp_gt_f32_e32 vcc, s91, v97
	v_cmp_gt_f32_e64 s[0:1], s91, v96
	s_and_saveexec_b64 s[56:57], s[8:9]
	s_cbranch_execz .LBB0_1141
	s_waitcnt lgkmcnt(2)
	v_mov_b32_e32 v108, v107
	v_mov_b32_e32 v109, v106
	s_waitcnt lgkmcnt(0)
	v_mov_b32_e32 v112, v105
	v_mov_b32_e32 v113, v104

.LBB0_1143:
	s_or_b64 exec, exec, s[0:1]
	v_pk_mul_f32 v[84:85], v[84:85], v[96:97]
	v_pk_mul_f32 v[80:81], v[80:81], v[96:97]
	s_waitcnt lgkmcnt(3)
	v_fma_f32 v98, v185, v84, v183
	v_fmac_f32_e32 v98, v184, v85
	v_fmac_f32_e32 v98, v186, v86
	s_waitcnt lgkmcnt(2)
	v_mul_f32_e32 v99, 0xbfb8aa3b, v98
	v_exp_f32_e32 v99, v99
	s_waitcnt lgkmcnt(0)
	v_fma_f32 v112, v185, v108, v183
	v_fmac_f32_e32 v112, v184, v84
	v_fmac_f32_e32 v112, v186, v85
	v_add_f32_e32 v96, 1.0, v99
	v_div_scale_f32 v97, s[0:1], v96, v96, v98
	v_rcp_f32_e32 v99, v97
	v_fma_f32 v102, v145, v80, v182
	v_fmac_f32_e32 v102, v141, v81
	v_fmac_f32_e32 v102, v181, v82
	v_fma_f32 v103, -v97, v99, 1.0
	v_fmac_f32_e32 v99, v103, v99
	v_div_scale_f32 v103, vcc, v98, v96, v98
	v_mul_f32_e32 v110, v103, v99
	v_fma_f32 v111, -v97, v110, v103
	v_fmac_f32_e32 v110, v111, v99
	v_fma_f32 v97, -v97, v110, v103
	v_fma_f32 v103, v185, v85, v183
	v_fmac_f32_e32 v103, v184, v86
	v_fmac_f32_e32 v103, v186, v87
	v_mul_f32_e32 v111, 0xbfb8aa3b, v103
	v_exp_f32_e32 v111, v111
	v_div_fmas_f32 v97, v97, v99, v110
	v_div_fixup_f32 v96, v97, v96, v98
	v_mul_f32_e32 v85, 0xbfb8aa3b, v112
	v_add_f32_e32 v97, 1.0, v111
	v_div_scale_f32 v98, s[0:1], v97, v97, v103
	v_rcp_f32_e32 v99, v98
	v_exp_f32_e32 v85, v85
	v_mul_f32_e32 v96, v102, v96
	v_fma_f32 v102, v145, v81, v182
	v_fma_f32 v110, -v98, v99, 1.0
	v_fmac_f32_e32 v99, v110, v99
	v_div_scale_f32 v110, vcc, v103, v97, v103
	v_mul_f32_e32 v111, v110, v99
	v_fma_f32 v113, -v98, v111, v110
	v_fmac_f32_e32 v111, v113, v99
	v_add_f32_e32 v85, 1.0, v85
	v_fma_f32 v98, -v98, v111, v110
	v_div_scale_f32 v110, s[0:1], v85, v85, v112
	v_rcp_f32_e32 v113, v110
	v_div_fmas_f32 v98, v98, v99, v111
	v_div_fixup_f32 v97, v98, v97, v103
	v_fmac_f32_e32 v102, v141, v82
	v_fma_f32 v98, -v110, v113, 1.0
	v_fmac_f32_e32 v113, v98, v113
	v_div_scale_f32 v98, vcc, v112, v85, v112
	v_fmac_f32_e32 v102, v181, v83
	v_mul_f32_e32 v99, v98, v113
	v_mul_f32_e32 v97, v102, v97
	v_fma_f32 v102, -v110, v99, v98
	v_fmac_f32_e32 v99, v102, v113
	v_fma_f32 v102, v185, v109, v183
	v_fmac_f32_e32 v102, v184, v108
	v_fmac_f32_e32 v102, v186, v84
	v_mul_f32_e32 v84, 0xbfb8aa3b, v102
	v_exp_f32_e32 v84, v84
	v_fma_f32 v98, -v110, v99, v98
	v_div_fmas_f32 v98, v98, v113, v99
	v_div_fixup_f32 v85, v98, v85, v112
	v_add_f32_e32 v84, 1.0, v84
	v_div_scale_f32 v99, s[0:1], v84, v84, v102
	v_rcp_f32_e32 v103, v99
	v_fma_f32 v98, v145, v100, v182
	v_fmac_f32_e32 v98, v141, v80
	v_fmac_f32_e32 v98, v181, v81
	v_mul_f32_e32 v81, v98, v85
	v_fma_f32 v85, -v99, v103, 1.0
	v_fmac_f32_e32 v103, v85, v103
	v_div_scale_f32 v85, vcc, v102, v84, v102
	v_mul_f32_e32 v98, v85, v103
	v_fma_f32 v108, -v99, v98, v85
	v_fmac_f32_e32 v98, v108, v103
	v_fma_f32 v85, -v99, v98, v85
	v_div_fmas_f32 v85, v85, v103, v98
	v_div_fixup_f32 v84, v85, v84, v102
	v_fma_f32 v85, v145, v101, v182
	v_fmac_f32_e32 v85, v141, v100
	v_fmac_f32_e32 v85, v181, v80
	v_mul_f32_e32 v80, v85, v84
	v_cvt_pk_bf16_f32 v80, v80, s0
	global_store_short v[88:89], v80, off offset:32
	v_cvt_pk_bf16_f32 v80, v81, s0
	global_store_short v[92:93], v80, off offset:3104
	v_cvt_pk_bf16_f32 v80, v96, s0
	global_store_short v[104:105], v80, off offset:2080
	v_cvt_pk_bf16_f32 v80, v97, s0
	global_store_short v[106:107], v80, off offset:1056
	v_mov_b32_e32 v96, v232
	v_mov_b32_e32 v97, v233
	v_mov_b32_e32 v98, v234
	v_mov_b32_e32 v99, v235
	v_mov_b64_e32 v[100:101], s[46:47]
	ds_bpermute_b32 v94, v191, v94
	ds_bpermute_b32 v95, v191, v95
	ds_bpermute_b32 v90, v191, v90
	ds_bpermute_b32 v91, v191, v91
	v_pk_fma_f32 v[80:81], v[98:99], s[42:43], v[100:101] op_sel_hi:[1,0,0]
	s_nop 0
	v_mul_f32_e32 v84, 0x4b800000, v80
	v_cmp_gt_f32_e32 vcc, s91, v80
	v_cmp_gt_f32_e64 s[0:1], s91, v81
	s_nop 0
	v_cndmask_b32_e32 v80, v80, v84, vcc
	v_mul_f32_e32 v84, 0x4b800000, v81
	v_cndmask_b32_e64 v81, v81, v84, s[0:1]
	v_rsq_f32_e32 v80, v80
	v_rsq_f32_e32 v81, v81
	s_nop 0
	v_pk_mul_f32 v[84:85], v[80:81], s[44:45] op_sel_hi:[1,0]
	s_nop 0
	v_cndmask_b32_e64 v81, v81, v85, s[0:1]
	v_cndmask_b32_e32 v80, v80, v84, vcc
	v_pk_mul_f32 v[84:85], v[78:79], v[80:81]
	v_pk_mul_f32 v[78:79], v[74:75], v[80:81]
	ds_bpermute_b32 v93, v191, v84
	ds_bpermute_b32 v92, v191, v85
	ds_bpermute_b32 v89, v191, v78
	ds_bpermute_b32 v88, v191, v79
	v_pk_fma_f32 v[74:75], v[96:97], s[42:43], v[100:101] op_sel_hi:[1,0,0]
	s_nop 0
	v_cmp_gt_f32_e32 vcc, s91, v75
	v_cmp_gt_f32_e64 s[0:1], s91, v74
	s_and_saveexec_b64 s[56:57], s[8:9]
	s_cbranch_execz .LBB0_1145
	s_waitcnt lgkmcnt(0)
	v_mov_b32_e32 v88, v91
	v_mov_b32_e32 v89, v90
	v_mov_b32_e32 v92, v95
	v_mov_b32_e32 v93, v94

	.amdhsa_kernel _Z8fwd_mega4Args
		.amdhsa_group_segment_fixed_size 0
		.amdhsa_private_segment_fixed_size 0
		.amdhsa_kernarg_size 560
		.amdhsa_user_sgpr_count 2
		.amdhsa_user_sgpr_dispatch_ptr 0
		.amdhsa_user_sgpr_queue_ptr 0
		.amdhsa_user_sgpr_kernarg_segment_ptr 1
		.amdhsa_user_sgpr_dispatch_id 0
		.amdhsa_user_sgpr_kernarg_preload_length 0
		.amdhsa_user_sgpr_kernarg_preload_offset 0
		.amdhsa_user_sgpr_private_segment_size 0
		.amdhsa_uses_dynamic_stack 0
		.amdhsa_enable_private_segment 0
		.amdhsa_system_sgpr_workgroup_id_x 1
		.amdhsa_system_sgpr_workgroup_id_y 0
		.amdhsa_system_sgpr_workgroup_id_z 0
		.amdhsa_system_sgpr_workgroup_info 0
		.amdhsa_system_vgpr_workitem_id 2
		.amdhsa_next_free_vgpr 238
		.amdhsa_next_free_sgpr 102
		.amdhsa_accum_offset 240
		.amdhsa_reserve_vcc 1
		.amdhsa_float_round_mode_32 0
		.amdhsa_float_round_mode_16_64 0
		.amdhsa_float_denorm_mode_32 3
		.amdhsa_float_denorm_mode_16_64 3
		.amdhsa_dx10_clamp 1
		.amdhsa_ieee_mode 1
		.amdhsa_fp16_overflow 0
		.amdhsa_tg_split 0
		.amdhsa_exception_fp_ieee_invalid_op 0
		.amdhsa_exception_fp_denorm_src 0
		.amdhsa_exception_fp_ieee_div_zero 0
		.amdhsa_exception_fp_ieee_overflow 0
		.amdhsa_exception_fp_ieee_underflow 0
		.amdhsa_exception_fp_ieee_inexact 0
		.amdhsa_exception_int_div_zero 0
	.end_amdhsa_kernel

amdhsa.kernels:
  - .agpr_count:     0
    .args:
      - .offset:         0
        .size:           304
        .value_kind:     by_value
      - .offset:         304
        .size:           4
        .value_kind:     hidden_block_count_x
      - .offset:         308
        .size:           4
        .value_kind:     hidden_block_count_y
      - .offset:         312
        .size:           4
        .value_kind:     hidden_block_count_z
      - .offset:         316
        .size:           2
        .value_kind:     hidden_group_size_x
      - .offset:         318
        .size:           2
        .value_kind:     hidden_group_size_y
      - .offset:         320
        .size:           2
        .value_kind:     hidden_group_size_z
      - .offset:         322
        .size:           2
        .value_kind:     hidden_remainder_x
      - .offset:         324
        .size:           2
        .value_kind:     hidden_remainder_y
      - .offset:         326
        .size:           2
        .value_kind:     hidden_remainder_z
      - .offset:         344
        .size:           8
        .value_kind:     hidden_global_offset_x
      - .offset:         352
        .size:           8
        .value_kind:     hidden_global_offset_y
      - .offset:         360
        .size:           8
        .value_kind:     hidden_global_offset_z
      - .offset:         368
        .size:           2
        .value_kind:     hidden_grid_dims
      - .offset:         392
        .size:           8
        .value_kind:     hidden_multigrid_sync_arg
      - .offset:         424
        .size:           4
        .value_kind:     hidden_dynamic_lds_size
    .group_segment_fixed_size: 0
    .kernarg_segment_align: 8
    .kernarg_segment_size: 560
    .language:       OpenCL C
    .language_version:
      - 2
      - 0
    .max_flat_workgroup_size: 512
    .name:           _Z8fwd_mega4Args
    .private_segment_fixed_size: 0
    .sgpr_count:     108
    .sgpr_spill_count: 117
    .symbol:         _Z8fwd_mega4Args.kd
    .uniform_work_group_size: 1
    .uses_dynamic_stack: false
    .vgpr_count:     238
    .vgpr_spill_count: 0
    .wavefront_size: 64
